# P5 K-loop: LDS tile relayout so that every LDS-DMA instruction fetches 8 full 128-byte lines instead of 16 half lines
# baseline (speedup 1.0000x reference)
; #define LAS __attribute__((address_space(3)))
; #define PG8_STAGEA(bufoff, gbase) PG8_STAGE_(bufoff, gbase, voffA)
; #define PG8_STAGEB(bufoff, gbase) PG8_STAGE_(bufoff, gbase, voffB)
; template <int EK, int SK = -1>
; __device__ __forceinline__ void gemm_phase(LAS unsigned char* lds, const bf16_t* A, const bf16_t* Bt, int nM, int N, int K, const EpiArgs& E) {
;     ...
;     unsigned voffA[2], voffB[2];
; #pragma unroll
;     for (int i = 0; i < 2; ++i) { int R, C; stage_rc(tid * 16 + i * 8192, R, C); const int Rb = (R & ~31) + perm32(R & 31);
;         voffA[i] = (unsigned)(R * K + C) * 2u; voffB[i] = (unsigned)(Rb * K + C) * 2u; }
;     const size_t kstep = (size_t)(BK * 2);
;     const size_t hstep = (size_t)HALF * K * 2;
;     const size_t tstep = 2 * hstep;
;     const unsigned ldsw = (unsigned)wid * 1024u;
;     const int aoff = lds_byte(wr * 64 + fr, fq * 8), boff = lds_byte(wc * 32 + fr, fq * 8);
;     ...
;     Unit cur, nxt; int ui = 0;
;     if (!S.next(0, cur)) { if (SK >= 0) skinny_phase<(SK >= 0 ? SK : 0)>(lds + 32768, (LAS float*)(lds + SRED_OFF), A, Bt, N, K, E); return; }
;     f32x4 acc[2][2][4][2];
; #pragma unroll
;     for (int a = 0; a < 2; ++a)
; #pragma unroll
;         for (int b = 0; b < 2; ++b)
; #pragma unroll
;             for (int m = 0; m < 4; ++m)
; #pragma unroll
;                 for (int n = 0; n < 2; ++n) acc[a][b][m][n] = (f32x4){0.f, 0.f, 0.f, 0.f};
;     bf16x8 At[4][2], B0[2][2], B1[2][2];
;     const char* cA = (const char*)A + (size_t)cur.pm * tstep; const char* cB = (const char*)Bt + (size_t)cur.pn * tstep;
;     PG8_STAGEB(PG8_SB(0, 0), cB); PG8_STAGEB(PG8_SB(0, 1), cB + hstep); PG8_STAGEA(PG8_SA(0, 0), cA); PG8_STAGEA(PG8_SA(0, 1), cA + hstep);
;     f32x4 tq[4][4]; bool okq[4];
;     if (EK != EK_RES && EK != EK_FINAL) {
; #pragma unroll
;         for (int j = 0; j < 4; ++j) { Unit uu; okq[j] = S.next((tid >> 8) + 2 * j, uu);
;             if (okq[j]) { const f32x4* sp = (const f32x4*)(E.stIn + (size_t)(uu.pm * BM + (tid & 255)) * 16); tq[j][0] = sp[0]; tq[j][1] = sp[1]; tq[j][2] = sp[2]; tq[j][3] = sp[3]; } }
.LBB0_766:
	s_waitcnt lgkmcnt(0)
	s_load_dword s44, s[0:1], 0xb8
	s_andn2_b64 vcc, exec, s[4:5]
	s_cbranch_vccnz .LBB0_817
	v_lshlrev_b32_e32 v1, 4, v0
	s_waitcnt vmcnt(0)
	v_and_b32_e32 v2, 32, v0
	v_bitop3_b32 v12, v1, v2, 48 bitop3:0x6c
	v_lshrrev_b32_e32 v2, 1, v0
	v_lshrrev_b32_e32 v4, 5, v0
	v_and_b32_e32 v2, 24, v2
	v_and_b32_e32 v4, 4, v4
	v_bfe_u32 v5, v0, 2, 2
	v_bfe_u32 v3, v0, 2, 4
	v_and_b32_e32 v13, 64, v0
	v_or3_b32 v2, v4, v5, v2
	v_lshrrev_b32_e32 v4, 3, v0
	v_or_b32_e32 v1, v12, v13
	v_and_or_b32 v5, v4, 48, v3
	v_and_or_b32 v4, v4, 32, v2
	v_lshrrev_b32_e32 v1, 1, v1
	v_mul_u32_u24_e32 v4, 0xb00, v4
	v_or_b32_e32 v4, v4, v1
	s_add_u32 s52, s30, 0x1100000
	v_bfe_u32 v4, v0, 3, 25
	s_addc_u32 s53, s31, 0
	s_lshr_b32 s22, s26, 6
	v_or_b32_e32 v4, 64, v4
	s_movk_i32 s4, 0x70
	v_and_or_b32 v3, v4, s4, v3
	s_movk_i32 s4, 0x60
	s_lshl_b32 s54, s22, 10
	s_mul_i32 s5, s45, 0x160000
	v_and_or_b32 v2, v4, s4, v2
	s_mul_hi_i32 s4, s45, 0x160000
	s_add_u32 s38, s52, s5
	s_addc_u32 s39, s53, s4
	s_add_i32 s55, s54, 0
	v_mul_u32_u24_e32 v14, 0xb00, v5
	v_mul_u32_u24_e32 v15, 0xb00, v3
	v_mul_u32_u24_e32 v2, 0xb00, v2
	s_add_i32 m0, s55, 0x10000
	v_or_b32_e32 v5, v1, v14
	v_or_b32_e32 v3, v15, v1
	v_or_b32_e32 v1, v2, v1
	v_lshrrev_b32_e32 v232, 3, v0
	v_xor_b32_e32 v233, v0, v232
	v_and_b32_e32 v233, 7, v233
	v_lshlrev_b32_e32 v233, 4, v233
	v_bfe_u32 v234, v0, 3, 2
	v_bfe_u32 v235, v0, 7, 1
	v_lshl_or_b32 v234, v235, 2, v234
	v_bfe_u32 v235, v0, 5, 1
	v_lshl_or_b32 v234, v235, 3, v234
	v_bfe_u32 v235, v0, 6, 1
	v_lshl_or_b32 v234, v235, 4, v234
	v_bfe_u32 v235, v0, 8, 1
	v_lshl_or_b32 v234, v235, 5, v234
	v_mul_u32_u24_e32 v232, 0x1600, v232
	v_mul_u32_u24_e32 v234, 0x1600, v234
	v_add_u32_e32 v130, v232, v233
	v_add_u32_e32 v132, v234, v233
	v_add_u32_e32 v134, 0x58000, v130
	v_add_u32_e32 v136, 0x58000, v132
	global_load_lds_dwordx4 v132, s[38:39]
	s_add_i32 m0, s55, 0x12000
	s_add_u32 s4, s38, 0xb0000
	global_load_lds_dwordx4 v136, s[38:39]
	s_addc_u32 s5, s39, 0
	s_add_i32 m0, s55, 0x14000
	s_mul_i32 s7, s3, 0x160000
	global_load_lds_dwordx4 v132, s[4:5]
	s_add_i32 m0, s55, 0x16000
	s_mul_hi_i32 s6, s3, 0x160000
	s_add_u32 s14, s64, s7
	s_addc_u32 s15, s65, s6
	s_add_i32 s56, s55, 0x2000
	global_load_lds_dwordx4 v136, s[4:5]
	s_mov_b32 m0, s55
	s_add_u32 s4, s14, 0xb0000
	global_load_lds_dwordx4 v130, s[14:15]
	s_mov_b32 m0, s56
	s_addc_u32 s5, s15, 0
	s_add_i32 s57, s55, 0x4000
	global_load_lds_dwordx4 v134, s[14:15]
	s_mov_b32 m0, s57
	s_add_i32 s58, s55, 0x6000
	global_load_lds_dwordx4 v130, s[4:5]
	s_mov_b32 m0, s58
	v_mov_b32_e32 v3, 0
	global_load_lds_dwordx4 v134, s[4:5]
	v_and_b32_e32 v16, 15, v0
	s_mov_b32 s11, 0
	v_mov_b32_e32 v133, v3
	v_mov_b32_e32 v137, v3
	v_mov_b32_e32 v131, v3
	v_mov_b32_e32 v135, v3
	s_cmpk_gt_i32 s2, 0x7f
	v_readfirstlane_b32 s6, v0
	s_cbranch_scc1 .LBB0_778
	s_lshr_b32 s7, s6, 6
	s_mul_i32 s10, s7, 0x160
	s_add_i32 s18, 0, 0x22010
	s_lshl_b64 s[4:5], s[10:11], 1
	s_add_u32 s8, s64, s4
	s_addc_u32 s9, s65, s5
	s_add_u32 s4, s52, s4
	s_addc_u32 s5, s53, s5
	v_and_b32_e32 v8, 63, v0
	v_and_b32_e32 v2, 48, v0
	s_cmpk_lt_u32 s6, 0x100
	v_lshl_add_u32 v9, v8, 4, 0
	v_lshl_add_u64 v[4:5], s[8:9], 0, v[2:3]
	v_lshl_add_u64 v[6:7], s[4:5], 0, v[2:3]
	s_cselect_b64 s[8:9], -1, 0
	v_lshrrev_b32_e32 v1, 2, v0
	s_and_b32 s4, s6, 0xc0
	s_lshl_b32 s10, s7, 4
	v_and_b32_e32 v2, 12, v1
	v_lshl_add_u32 v1, s4, 4, v9
	v_cmp_gt_u32_e64 s[4:5], 16, v8
	s_andn2_b32 s6, s6, 63
	v_cndmask_b32_e64 v8, 0, 1, s[8:9]
	s_lshl_b32 s19, s7, 12
	v_or_b32_e32 v17, s10, v2
	s_add_i32 s6, s6, s18
	v_cmp_ne_u32_e64 s[8:9], 1, v8
	v_lshlrev_b32_e32 v8, 1, v2
	v_mbcnt_lo_u32_b32 v2, -1, 0
	v_lshl_add_u32 v18, v16, 2, s6
	v_cmp_gt_u32_e64 s[6:7], 16, v0
	v_lshl_add_u32 v19, v0, 2, s18
	s_lshl_b32 s23, s2, 4
	s_waitcnt lgkmcnt(0)
	s_lshl_b32 s27, s44, 4
	s_lshl_b32 s10, s10, 1
	s_movk_i32 s36, 0x1600
	v_add_u32_e32 v20, s19, v9
	v_mbcnt_hi_u32_b32 v21, -1, v2
	s_mov_b32 s37, s2
	s_branch .LBB0_770

; #define LAS __attribute__((address_space(3)))
; __device__ __forceinline__ float hsum4(f32x4 v) { return (v[0] + v[1]) + (v[2] + v[3]); }
; #define PG8_STAGEA(bufoff, gbase) PG8_STAGE_(bufoff, gbase, voffA)
; #define PG8_STAGEB(bufoff, gbase) PG8_STAGE_(bufoff, gbase, voffB)
; template <int EK, int SK = -1>
; __device__ __forceinline__ void gemm_phase(LAS unsigned char* lds, const bf16_t* A, const bf16_t* Bt, int nM, int N, int K, const EpiArgs& E) {
;     ...
;     const int aoff = lds_byte(wr * 64 + fr, fq * 8), boff = lds_byte(wc * 32 + fr, fq * 8);
;     ...
;     Unit cur, nxt; int ui = 0;
;     if (!S.next(0, cur)) { if (SK >= 0) skinny_phase<(SK >= 0 ? SK : 0)>(lds + 32768, (LAS float*)(lds + SRED_OFF), A, Bt, N, K, E); return; }
;     f32x4 acc[2][2][4][2];
; #pragma unroll
;     for (int a = 0; a < 2; ++a)
; #pragma unroll
;         for (int b = 0; b < 2; ++b)
; #pragma unroll
;             for (int m = 0; m < 4; ++m)
; #pragma unroll
;                 for (int n = 0; n < 2; ++n) acc[a][b][m][n] = (f32x4){0.f, 0.f, 0.f, 0.f};
;     bf16x8 At[4][2], B0[2][2], B1[2][2];
;     const char* cA = (const char*)A + (size_t)cur.pm * tstep; const char* cB = (const char*)Bt + (size_t)cur.pn * tstep;
;     PG8_STAGEB(PG8_SB(0, 0), cB); PG8_STAGEB(PG8_SB(0, 1), cB + hstep); PG8_STAGEA(PG8_SA(0, 0), cA); PG8_STAGEA(PG8_SA(0, 1), cA + hstep);
;     f32x4 tq[4][4]; bool okq[4];
;     if (EK != EK_RES && EK != EK_FINAL) {
; #pragma unroll
;         for (int j = 0; j < 4; ++j) { Unit uu; okq[j] = S.next((tid >> 8) + 2 * j, uu);
;             if (okq[j]) { const f32x4* sp = (const f32x4*)(E.stIn + (size_t)(uu.pm * BM + (tid & 255)) * 16); tq[j][0] = sp[0]; tq[j][1] = sp[1]; tq[j][2] = sp[2]; tq[j][3] = sp[3]; } }
;     }
;     if (SK >= 0) skinny_phase<(SK >= 0 ? SK : 0)>(lds + 32768, (LAS float*)(lds + SRED_OFF), A, Bt, N, K, E);
;     if (EK != EK_RES && EK != EK_FINAL) {
; #pragma unroll
;         for (int j = 0; j < 4; ++j) if (okq[j]) { const float s_ = (hsum4(tq[j][0]) + hsum4(tq[j][1])) + (hsum4(tq[j][2]) + hsum4(tq[j][3]));
;             rtab[((tid >> 8) + 2 * j) * 256 + (tid & 255)] = rsqrtf(s_ * (1.0f / 1024.0f) + EPS); }
;         __syncthreads();
;     }
;     if (wr == 1) PG8_BAR;
;     PG8_WAIT_V(2); PG8_BAR;
;     PG8_STAGEB(PG8_SB(1, 0), cB + kstep); PG8_STAGEA(PG8_SA(1, 0), cA + kstep); PG8_STAGEB(PG8_SB(1, 1), cB + hstep + kstep);
;     PG8_WAIT_V(6); PG8_BAR;
.LBB0_780:
	v_bfe_u32 v10, v0, 4, 2
	v_lshlrev_b32_e32 v17, 4, v10
	v_lshl_or_b32 v1, s4, 6, v16
	v_lshl_or_b32 v18, v16, 6, v17
	v_lshlrev_b32_e32 v16, 2, v16
	s_lshl_b32 s4, s4, 13
	v_and_b32_e32 v16, 32, v16
	s_and_b32 s59, s22, 3
	v_bitop3_b32 v16, v18, s4, v16 bitop3:0xde
	v_lshlrev_b32_e32 v18, 6, v0
	s_movk_i32 s4, 0x3c0
	s_mov_b64 s[22:23], 0x80
	v_and_or_b32 v17, v18, s4, v17
	v_lshlrev_b32_e32 v18, 2, v0
	s_add_i32 m0, s55, 0x18000
	v_lshl_add_u64 v[8:9], v[8:9], 0, s[22:23]
	s_lshl_b32 s4, s59, 12
	v_and_b32_e32 v18, 32, v18
	s_ashr_i32 s68, s2, 31
	s_waitcnt vmcnt(2)
	s_barrier
	global_load_lds_dwordx4 v[8:9], off
	v_lshl_add_u64 v[6:7], v[6:7], 0, s[22:23]
	s_add_i32 m0, s55, 0x1a000
	s_add_i32 s69, s55, 0x8000
	s_add_i32 s70, s55, 0xa000
	v_and_b32_e32 v232, 15, v0
	v_bfe_u32 v233, v0, 4, 2
	v_and_b32_e32 v234, 7, v232
	v_xor_b32_e32 v233, v233, v234
	v_lshlrev_b32_e32 v233, 4, v233
	v_lshl_or_b32 v233, v234, 7, v233
	v_lshrrev_b32_e32 v232, 3, v232
	v_bfe_u32 v234, v0, 6, 2
	v_lshl_or_b32 v234, v234, 2, v232
	v_lshl_or_b32 v152, v234, 10, v233
	v_xor_b32_e32 v239, 64, v152
	global_load_lds_dwordx4 v[6:7], off
	v_lshl_add_u64 v[2:3], v[2:3], 0, s[22:23]
	s_mov_b32 m0, s69
	s_add_u32 s4, s38, 0xb0080
	global_load_lds_dwordx4 v[2:3], off
	v_lshl_add_u64 v[2:3], v[4:5], 0, s[22:23]
	s_mov_b32 m0, s70
	s_addc_u32 s5, s39, 0
	global_load_lds_dwordx4 v[2:3], off
	s_add_i32 m0, s55, 0x1c000
	v_lshl_add_u64 v[2:3], s[4:5], 0, v[132:133]
	global_load_lds_dwordx4 v[2:3], off
	v_lshl_add_u64 v[2:3], s[4:5], 0, v[136:137]
	s_add_i32 m0, s55, 0x1e000
	s_mov_b64 s[6:7], 0xb0080
	global_load_lds_dwordx4 v[2:3], off
	v_add_u16_e32 v2, v12, v13
	v_lshrrev_b16_e32 v4, 1, v2
	v_add_lshl_u32 v2, v14, v4, 1
	v_mov_b32_e32 v3, 0
	s_waitcnt vmcnt(6)
	v_lshl_add_u64 v[138:139], v[130:131], 0, s[6:7]
	v_add_lshl_u32 v2, v15, v4, 1
	v_lshlrev_b32_e32 v11, 3, v10
	s_cmpk_lt_u32 s26, 0x100
	v_lshl_add_u64 v[140:141], v[134:135], 0, s[6:7]
	v_mbcnt_lo_u32_b32 v2, -1, 0
	s_mov_b32 s21, 0
	v_lshl_or_b32 v153, s59, 5, v11
	s_cselect_b64 s[26:27], -1, 0
	v_cmp_eq_u32_e64 s[4:5], 0, v10
	v_mov_b64_e32 v[142:143], 0x100
	v_mov_b64_e32 v[144:145], 0xff
	s_add_i32 s71, 0, 0x10000
	s_add_i32 s72, 0, 0x14000
	v_and_b32_e32 v232, 15, v0
	v_bfe_u32 v233, v0, 4, 2
	v_and_b32_e32 v234, 7, v232
	v_xor_b32_e32 v233, v233, v234
	v_lshlrev_b32_e32 v233, 4, v233
	v_lshl_or_b32 v233, v234, 7, v233
	v_lshrrev_b32_e32 v232, 3, v232
	v_lshrrev_b32_e32 v234, 8, v0
	v_lshl_or_b32 v234, v234, 3, v232
	v_lshl_or_b32 v154, v234, 10, v233
	v_xor_b32_e32 v238, 64, v154
	v_mbcnt_hi_u32_b32 v155, -1, v2
	s_mov_b32 s75, 0
	v_mov_b32_e32 v2, v3
	s_barrier
	s_branch .LBB0_782

; #define PG8_STAGEA(bufoff, gbase) PG8_STAGE_(bufoff, gbase, voffA)
; #define PG8_STAGEB(bufoff, gbase) PG8_STAGE_(bufoff, gbase, voffB)
; #define PG8_LDA(dst, b, h) do { _Pragma("unroll") for (int m = 0; m < 4; ++m) _Pragma("unroll") for (int k = 0; k < 2; ++k) dst[m][k] = *(const LAS bf16x8*)(lds + PG8_SA(b, h) + aoff + m * 2048 + k * 1024); } while (0)
; #define PG8_LDB(dst, b, h) do { _Pragma("unroll") for (int n = 0; n < 2; ++n) _Pragma("unroll") for (int k = 0; k < 2; ++k) dst[n][k] = *(const LAS bf16x8*)(lds + PG8_SB(b, h) + boff + n * 2048 + k * 1024); } while (0)
; #define PG8_MMA(ai, bj, At, Bt_) do { __builtin_amdgcn_s_setprio(1); _Pragma("unroll") for (int m = 0; m < 4; ++m) _Pragma("unroll") for (int n = 0; n < 2; ++n) _Pragma("unroll") for (int k = 0; k < 2; ++k) \
;         acc[ai][bj][m][n] = __builtin_amdgcn_mfma_f32_16x16x32_bf16(Bt_[n][k], At[m][k], acc[ai][bj][m][n], 0, 0, 0); __builtin_amdgcn_s_setprio(0); } while (0)
; #define PG8_WAIT_V(n) asm volatile("s_waitcnt vmcnt(" #n ")" ::: "memory")
; #define PG8_WAIT_L(n) asm volatile("s_waitcnt lgkmcnt(" #n ")" ::: "memory")
; #define PG8_BAR __builtin_amdgcn_s_barrier()
; template <int EK, int SK = -1>
; __device__ __forceinline__ void gemm_phase(LAS unsigned char* lds, const bf16_t* A, const bf16_t* Bt, int nM, int N, int K, const EpiArgs& E) {
;     ...
;         const bool has_next = S.next(ui + 1, nxt);
;         const char* nA = has_next ? (const char*)A + (size_t)nxt.pm * tstep : cA; const char* nB = has_next ? (const char*)Bt + (size_t)nxt.pn * tstep : cB;
;         for (int t = 0; t < nt; t += 2) {
;             const bool last = (t == nt - 2);
;             const char* a1 = cA + (size_t)(t + 1) * kstep;
;             const char* a2 = last ? nA : cA + (size_t)(t + 2) * kstep; const char* b2 = last ? nB : cB + (size_t)(t + 2) * kstep;
;             const char* a3 = a2 + kstep; const char* b3 = b2 + kstep;
;             PG8_LDB(B0, 0, 0); PG8_LDB(B1, 0, 1); PG8_SCHED; PG8_LDA(At, 0, 0); PG8_STAGEA(PG8_SA(1, 1), a1 + hstep);
;             PG8_WAIT_V(8); PG8_WAIT_L(0); PG8_BAR; PG8_MMA(0, 0, At, B0); PG8_MMA(0, 1, At, B1); PG8_BAR; PG8_SCHED;
;             PG8_LDA(At, 0, 1); PG8_STAGEB(PG8_SB(0, 0), b2); PG8_STAGEB(PG8_SB(0, 1), b2 + hstep); PG8_STAGEA(PG8_SA(0, 0), a2);
;             PG8_WAIT_V(8); PG8_WAIT_L(0); PG8_BAR; PG8_MMA(1, 0, At, B0); PG8_MMA(1, 1, At, B1); PG8_BAR; PG8_SCHED;
.LBB0_792:
	s_add_u32 s77, s38, 0x100
	s_addc_u32 s78, s39, 0
	v_lshl_add_u64 v[146:147], s[14:15], 0, v[138:139]
	v_lshl_add_u64 v[148:149], s[14:15], 0, v[140:141]
	s_mov_b32 s20, -2
	s_mov_b64 s[38:39], 0
	v_add_u32_e32 v150, s71, v152
	v_add_u32_e32 v237, s71, v239
	ds_read_b128 v[156:159], v150
	ds_read_b128 v[160:163], v237
	ds_read_b128 v[164:167], v150 offset:2048
	ds_read_b128 v[168:171], v237 offset:2048
	v_add_u32_e32 v150, s72, v152
	v_add_u32_e32 v237, s72, v239
	s_add_u32 s40, s14, s38
	ds_read_b128 v[172:175], v150
	ds_read_b128 v[176:179], v237
	ds_read_b128 v[180:183], v150 offset:2048
	ds_read_b128 v[184:187], v237 offset:2048
	s_addc_u32 s41, s15, s39
	s_add_u32 s40, s40, 0x100
	s_addc_u32 s41, s41, 0
	s_add_u32 s79, s77, s38
	s_addc_u32 s80, s78, s39
	s_cmpk_eq_i32 s38, 0x1500
	s_cselect_b32 s43, s37, s41
	s_cselect_b32 s42, s36, s40
	s_cselect_b32 s41, s11, s80
	s_cselect_b32 s40, s10, s79
	v_lshl_add_u64 v[150:151], v[146:147], 0, s[38:39]
	s_add_i32 m0, s55, 0xc000
	ds_read_b128 v[188:191], v154
	ds_read_b128 v[192:195], v238
	ds_read_b128 v[196:199], v154 offset:2048
	ds_read_b128 v[200:203], v238 offset:2048
	ds_read_b128 v[204:207], v154 offset:4096
	ds_read_b128 v[208:211], v238 offset:4096
	ds_read_b128 v[212:215], v154 offset:6144
	ds_read_b128 v[216:219], v238 offset:6144
	global_load_lds_dwordx4 v[150:151], off
	v_lshl_add_u64 v[150:151], v[148:149], 0, s[38:39]
	s_add_i32 m0, s55, 0xe000
	s_nop 0
	global_load_lds_dwordx4 v[150:151], off
	s_waitcnt vmcnt(8)
	s_waitcnt lgkmcnt(0)
	s_barrier
	s_waitcnt lgkmcnt(0)
	v_mfma_f32_16x16x32_bf16 v[126:129], v[156:159], v[188:191], 0
	v_mfma_f32_16x16x32_bf16 v[122:125], v[164:167], v[188:191], 0
	v_mfma_f32_16x16x32_bf16 v[118:121], v[156:159], v[196:199], 0
	v_mfma_f32_16x16x32_bf16 v[114:117], v[164:167], v[196:199], 0
	v_mfma_f32_16x16x32_bf16 v[110:113], v[156:159], v[204:207], 0
	v_mfma_f32_16x16x32_bf16 v[106:109], v[164:167], v[204:207], 0
	v_mfma_f32_16x16x32_bf16 v[102:105], v[156:159], v[212:215], 0
	v_mfma_f32_16x16x32_bf16 v[98:101], v[164:167], v[212:215], 0
	v_mfma_f32_16x16x32_bf16 v[126:129], v[160:163], v[192:195], v[126:129]
	v_mfma_f32_16x16x32_bf16 v[122:125], v[168:171], v[192:195], v[122:125]
	v_mfma_f32_16x16x32_bf16 v[118:121], v[160:163], v[200:203], v[118:121]
	v_mfma_f32_16x16x32_bf16 v[114:117], v[168:171], v[200:203], v[114:117]
	v_mfma_f32_16x16x32_bf16 v[110:113], v[160:163], v[208:211], v[110:113]
	v_mfma_f32_16x16x32_bf16 v[106:109], v[168:171], v[208:211], v[106:109]
	v_mfma_f32_16x16x32_bf16 v[102:105], v[160:163], v[216:219], v[102:105]
	v_mfma_f32_16x16x32_bf16 v[98:101], v[168:171], v[216:219], v[98:101]
	v_mfma_f32_16x16x32_bf16 v[94:97], v[172:175], v[188:191], 0
	v_mfma_f32_16x16x32_bf16 v[90:93], v[180:183], v[188:191], 0
	v_mfma_f32_16x16x32_bf16 v[86:89], v[172:175], v[196:199], 0
	v_mfma_f32_16x16x32_bf16 v[82:85], v[180:183], v[196:199], 0
	v_mfma_f32_16x16x32_bf16 v[78:81], v[172:175], v[204:207], 0
	v_mfma_f32_16x16x32_bf16 v[74:77], v[180:183], v[204:207], 0
	v_mfma_f32_16x16x32_bf16 v[70:73], v[172:175], v[212:215], 0
	v_mfma_f32_16x16x32_bf16 v[66:69], v[180:183], v[212:215], 0
	v_mfma_f32_16x16x32_bf16 v[94:97], v[176:179], v[192:195], v[94:97]
	v_mfma_f32_16x16x32_bf16 v[90:93], v[184:187], v[192:195], v[90:93]
	v_mfma_f32_16x16x32_bf16 v[86:89], v[176:179], v[200:203], v[86:89]
	v_mfma_f32_16x16x32_bf16 v[82:85], v[184:187], v[200:203], v[82:85]
	v_mfma_f32_16x16x32_bf16 v[78:81], v[176:179], v[208:211], v[78:81]
	v_mfma_f32_16x16x32_bf16 v[74:77], v[184:187], v[208:211], v[74:77]
	v_mfma_f32_16x16x32_bf16 v[70:73], v[176:179], v[216:219], v[70:73]
	v_mfma_f32_16x16x32_bf16 v[66:69], v[184:187], v[216:219], v[66:69]
	s_barrier
	s_add_i32 s79, s71, s54
	v_lshl_add_u64 v[150:151], s[40:41], 0, v[132:133]
	s_mov_b32 m0, s79
	ds_read_b128 v[188:191], v154 offset:16384
	ds_read_b128 v[192:195], v238 offset:16384
	ds_read_b128 v[196:199], v154 offset:18432
	ds_read_b128 v[200:203], v238 offset:18432
	ds_read_b128 v[204:207], v154 offset:20480
	ds_read_b128 v[208:211], v238 offset:20480
	ds_read_b128 v[212:215], v154 offset:22528
	ds_read_b128 v[216:219], v238 offset:22528
	global_load_lds_dwordx4 v[150:151], off
	s_add_i32 m0, s79, 0x2000
	s_add_u32 s80, s40, 0xb0000
	v_lshl_add_u64 v[220:221], s[40:41], 0, v[136:137]
	s_addc_u32 s81, s41, 0
	s_add_i32 s79, s72, s54
	global_load_lds_dwordx4 v[220:221], off
	v_lshl_add_u64 v[222:223], s[80:81], 0, v[132:133]
	s_mov_b32 m0, s79
	v_lshl_add_u64 v[224:225], s[42:43], 0, v[134:135]
	global_load_lds_dwordx4 v[222:223], off
	v_lshl_add_u64 v[222:223], s[80:81], 0, v[136:137]
	s_add_i32 m0, s79, 0x2000
	s_nop 0
	global_load_lds_dwordx4 v[222:223], off
	v_lshl_add_u64 v[222:223], s[42:43], 0, v[130:131]
	s_mov_b32 m0, s55
	s_nop 0
	global_load_lds_dwordx4 v[222:223], off
	s_mov_b32 m0, s56
	s_nop 0
	global_load_lds_dwordx4 v[224:225], off
	s_waitcnt vmcnt(8)
	s_waitcnt lgkmcnt(0)
	s_barrier
; #define PG8_STAGEA(bufoff, gbase) PG8_STAGE_(bufoff, gbase, voffA)
; #define PG8_STAGEB(bufoff, gbase) PG8_STAGE_(bufoff, gbase, voffB)
; #define PG8_LDA(dst, b, h) do { _Pragma("unroll") for (int m = 0; m < 4; ++m) _Pragma("unroll") for (int k = 0; k < 2; ++k) dst[m][k] = *(const LAS bf16x8*)(lds + PG8_SA(b, h) + aoff + m * 2048 + k * 1024); } while (0)
; #define PG8_LDB(dst, b, h) do { _Pragma("unroll") for (int n = 0; n < 2; ++n) _Pragma("unroll") for (int k = 0; k < 2; ++k) dst[n][k] = *(const LAS bf16x8*)(lds + PG8_SB(b, h) + boff + n * 2048 + k * 1024); } while (0)
; #define PG8_MMA(ai, bj, At, Bt_) do { __builtin_amdgcn_s_setprio(1); _Pragma("unroll") for (int m = 0; m < 4; ++m) _Pragma("unroll") for (int n = 0; n < 2; ++n) _Pragma("unroll") for (int k = 0; k < 2; ++k) \
;         acc[ai][bj][m][n] = __builtin_amdgcn_mfma_f32_16x16x32_bf16(Bt_[n][k], At[m][k], acc[ai][bj][m][n], 0, 0, 0); __builtin_amdgcn_s_setprio(0); } while (0)
; #define PG8_WAIT_V(n) asm volatile("s_waitcnt vmcnt(" #n ")" ::: "memory")
; #define PG8_WAIT_L(n) asm volatile("s_waitcnt lgkmcnt(" #n ")" ::: "memory")
; #define PG8_BAR __builtin_amdgcn_s_barrier()
; #define PG8_SCHED __builtin_amdgcn_sched_barrier(0)
; template <int EK, int SK = -1>
; __device__ __forceinline__ void gemm_phase(LAS unsigned char* lds, const bf16_t* A, const bf16_t* Bt, int nM, int N, int K, const EpiArgs& E) {
;     ...
;             PG8_WAIT_V(8); PG8_WAIT_L(0); PG8_BAR; PG8_MMA(1, 0, At, B0); PG8_MMA(1, 1, At, B1); PG8_BAR; PG8_SCHED;
;             PG8_LDB(B0, 1, 0); PG8_LDB(B1, 1, 1); PG8_SCHED; PG8_LDA(At, 1, 0); PG8_STAGEA(PG8_SA(0, 1), a2 + hstep);
;             PG8_WAIT_V(8); PG8_WAIT_L(0); PG8_BAR; PG8_MMA(0, 0, At, B0); PG8_MMA(0, 1, At, B1); PG8_BAR; PG8_SCHED;
;             PG8_LDA(At, 1, 1); PG8_STAGEB(PG8_SB(1, 0), b3); PG8_STAGEB(PG8_SB(1, 1), b3 + hstep); PG8_STAGEA(PG8_SA(1, 0), a3);
;             PG8_WAIT_V(8); PG8_WAIT_L(0); PG8_BAR; PG8_MMA(1, 0, At, B0); PG8_MMA(1, 1, At, B1); PG8_BAR; PG8_SCHED;
	s_waitcnt lgkmcnt(0)
	v_mfma_f32_16x16x32_bf16 v[62:65], v[156:159], v[188:191], 0
	v_mfma_f32_16x16x32_bf16 v[58:61], v[164:167], v[188:191], 0
	v_mfma_f32_16x16x32_bf16 v[54:57], v[156:159], v[196:199], 0
	v_mfma_f32_16x16x32_bf16 v[50:53], v[164:167], v[196:199], 0
	v_mfma_f32_16x16x32_bf16 v[46:49], v[156:159], v[204:207], 0
	v_mfma_f32_16x16x32_bf16 v[42:45], v[164:167], v[204:207], 0
	v_mfma_f32_16x16x32_bf16 v[38:41], v[156:159], v[212:215], 0
	v_mfma_f32_16x16x32_bf16 v[34:37], v[164:167], v[212:215], 0
	v_mfma_f32_16x16x32_bf16 v[62:65], v[160:163], v[192:195], v[62:65]
	v_mfma_f32_16x16x32_bf16 v[58:61], v[168:171], v[192:195], v[58:61]
	v_mfma_f32_16x16x32_bf16 v[54:57], v[160:163], v[200:203], v[54:57]
	v_mfma_f32_16x16x32_bf16 v[50:53], v[168:171], v[200:203], v[50:53]
	v_mfma_f32_16x16x32_bf16 v[46:49], v[160:163], v[208:211], v[46:49]
	v_mfma_f32_16x16x32_bf16 v[42:45], v[168:171], v[208:211], v[42:45]
	v_mfma_f32_16x16x32_bf16 v[38:41], v[160:163], v[216:219], v[38:41]
	v_mfma_f32_16x16x32_bf16 v[34:37], v[168:171], v[216:219], v[34:37]
	v_mfma_f32_16x16x32_bf16 v[30:33], v[172:175], v[188:191], 0
	v_mfma_f32_16x16x32_bf16 v[26:29], v[180:183], v[188:191], 0
	v_mfma_f32_16x16x32_bf16 v[22:25], v[172:175], v[196:199], 0
	v_mfma_f32_16x16x32_bf16 v[18:21], v[180:183], v[196:199], 0
	v_mfma_f32_16x16x32_bf16 v[14:17], v[172:175], v[204:207], 0
	v_mfma_f32_16x16x32_bf16 v[10:13], v[180:183], v[204:207], 0
	v_mfma_f32_16x16x32_bf16 v[6:9], v[172:175], v[212:215], 0
	v_mfma_f32_16x16x32_bf16 v[2:5], v[180:183], v[212:215], 0
	v_mfma_f32_16x16x32_bf16 v[30:33], v[176:179], v[192:195], v[30:33]
	v_mfma_f32_16x16x32_bf16 v[26:29], v[184:187], v[192:195], v[26:29]
	v_mfma_f32_16x16x32_bf16 v[22:25], v[176:179], v[200:203], v[22:25]
	v_mfma_f32_16x16x32_bf16 v[18:21], v[184:187], v[200:203], v[18:21]
	v_mfma_f32_16x16x32_bf16 v[14:17], v[176:179], v[208:211], v[14:17]
	v_mfma_f32_16x16x32_bf16 v[10:13], v[184:187], v[208:211], v[10:13]
	v_mfma_f32_16x16x32_bf16 v[6:9], v[176:179], v[216:219], v[6:9]
	v_mfma_f32_16x16x32_bf16 v[2:5], v[184:187], v[216:219], v[2:5]
	s_barrier
	s_add_i32 s79, 0, 0x18000
	s_add_i32 s80, 0, 0x1c000
	v_add_u32_e32 v168, s79, v152
	v_add_u32_e32 v236, s79, v239
	v_add_u32_e32 v184, s80, v152
	v_add_u32_e32 v237, s80, v239
	ds_read_b128 v[156:159], v168
	ds_read_b128 v[160:163], v236
	ds_read_b128 v[164:167], v168 offset:2048
	ds_read_b128 v[168:171], v236 offset:2048
	ds_read_b128 v[172:175], v184
	ds_read_b128 v[176:179], v237
	ds_read_b128 v[180:183], v184 offset:2048
	ds_read_b128 v[184:187], v237 offset:2048
	s_add_u32 s42, s42, 0xb0000
	s_addc_u32 s43, s43, 0
	s_mov_b32 m0, s57
	v_lshl_add_u64 v[226:227], s[42:43], 0, v[130:131]
	ds_read_b128 v[188:191], v154 offset:32768
	ds_read_b128 v[192:195], v238 offset:32768
	ds_read_b128 v[196:199], v154 offset:34816
	ds_read_b128 v[200:203], v238 offset:34816
	ds_read_b128 v[204:207], v154 offset:36864
	ds_read_b128 v[208:211], v238 offset:36864
	ds_read_b128 v[212:215], v154 offset:38912
	ds_read_b128 v[216:219], v238 offset:38912
	global_load_lds_dwordx4 v[226:227], off
	v_lshl_add_u64 v[226:227], s[42:43], 0, v[134:135]
	s_mov_b32 m0, s58
	s_nop 0
	global_load_lds_dwordx4 v[226:227], off
	s_waitcnt vmcnt(8)
	s_waitcnt lgkmcnt(0)
	s_barrier
	s_waitcnt lgkmcnt(0)
	v_mfma_f32_16x16x32_bf16 v[126:129], v[156:159], v[188:191], v[126:129]
	v_mfma_f32_16x16x32_bf16 v[122:125], v[164:167], v[188:191], v[122:125]
	v_mfma_f32_16x16x32_bf16 v[118:121], v[156:159], v[196:199], v[118:121]
	v_mfma_f32_16x16x32_bf16 v[114:117], v[164:167], v[196:199], v[114:117]
	v_mfma_f32_16x16x32_bf16 v[110:113], v[156:159], v[204:207], v[110:113]
	v_mfma_f32_16x16x32_bf16 v[106:109], v[164:167], v[204:207], v[106:109]
	v_mfma_f32_16x16x32_bf16 v[102:105], v[156:159], v[212:215], v[102:105]
	v_mfma_f32_16x16x32_bf16 v[98:101], v[164:167], v[212:215], v[98:101]
	v_mfma_f32_16x16x32_bf16 v[126:129], v[160:163], v[192:195], v[126:129]
	v_mfma_f32_16x16x32_bf16 v[122:125], v[168:171], v[192:195], v[122:125]
	v_mfma_f32_16x16x32_bf16 v[118:121], v[160:163], v[200:203], v[118:121]
	v_mfma_f32_16x16x32_bf16 v[114:117], v[168:171], v[200:203], v[114:117]
	v_mfma_f32_16x16x32_bf16 v[110:113], v[160:163], v[208:211], v[110:113]
	v_mfma_f32_16x16x32_bf16 v[106:109], v[168:171], v[208:211], v[106:109]
	v_mfma_f32_16x16x32_bf16 v[102:105], v[160:163], v[216:219], v[102:105]
	v_mfma_f32_16x16x32_bf16 v[98:101], v[168:171], v[216:219], v[98:101]
	v_mfma_f32_16x16x32_bf16 v[94:97], v[172:175], v[188:191], v[94:97]
	v_mfma_f32_16x16x32_bf16 v[90:93], v[180:183], v[188:191], v[90:93]
	v_mfma_f32_16x16x32_bf16 v[86:89], v[172:175], v[196:199], v[86:89]
	v_mfma_f32_16x16x32_bf16 v[82:85], v[180:183], v[196:199], v[82:85]
	v_mfma_f32_16x16x32_bf16 v[78:81], v[172:175], v[204:207], v[78:81]
	v_mfma_f32_16x16x32_bf16 v[74:77], v[180:183], v[204:207], v[74:77]
	v_mfma_f32_16x16x32_bf16 v[70:73], v[172:175], v[212:215], v[70:73]
	v_mfma_f32_16x16x32_bf16 v[66:69], v[180:183], v[212:215], v[66:69]
	v_mfma_f32_16x16x32_bf16 v[94:97], v[176:179], v[192:195], v[94:97]
	v_mfma_f32_16x16x32_bf16 v[90:93], v[184:187], v[192:195], v[90:93]
	v_mfma_f32_16x16x32_bf16 v[86:89], v[176:179], v[200:203], v[86:89]
	v_mfma_f32_16x16x32_bf16 v[82:85], v[184:187], v[200:203], v[82:85]
	v_mfma_f32_16x16x32_bf16 v[78:81], v[176:179], v[208:211], v[78:81]
	v_mfma_f32_16x16x32_bf16 v[74:77], v[184:187], v[208:211], v[74:77]
	v_mfma_f32_16x16x32_bf16 v[70:73], v[176:179], v[216:219], v[70:73]
	v_mfma_f32_16x16x32_bf16 v[66:69], v[184:187], v[216:219], v[66:69]
	s_barrier
; #define PG8_STAGEA(bufoff, gbase) PG8_STAGE_(bufoff, gbase, voffA)
; #define PG8_STAGEB(bufoff, gbase) PG8_STAGE_(bufoff, gbase, voffB)
; #define PG8_LDA(dst, b, h) do { _Pragma("unroll") for (int m = 0; m < 4; ++m) _Pragma("unroll") for (int k = 0; k < 2; ++k) dst[m][k] = *(const LAS bf16x8*)(lds + PG8_SA(b, h) + aoff + m * 2048 + k * 1024); } while (0)
; #define PG8_LDB(dst, b, h) do { _Pragma("unroll") for (int n = 0; n < 2; ++n) _Pragma("unroll") for (int k = 0; k < 2; ++k) dst[n][k] = *(const LAS bf16x8*)(lds + PG8_SB(b, h) + boff + n * 2048 + k * 1024); } while (0)
; #define PG8_WAIT_V(n) asm volatile("s_waitcnt vmcnt(" #n ")" ::: "memory")
; #define PG8_WAIT_L(n) asm volatile("s_waitcnt lgkmcnt(" #n ")" ::: "memory")
; #define PG8_BAR __builtin_amdgcn_s_barrier()
; #define PG8_SCHED __builtin_amdgcn_sched_barrier(0)
; template <int EK, int SK = -1>
; __device__ __forceinline__ void gemm_phase(LAS unsigned char* lds, const bf16_t* A, const bf16_t* Bt, int nM, int N, int K, const EpiArgs& E) {
;     ...
;         for (int t = 0; t < nt; t += 2) {
;             const bool last = (t == nt - 2);
;             const char* a1 = cA + (size_t)(t + 1) * kstep;
;             const char* a2 = last ? nA : cA + (size_t)(t + 2) * kstep; const char* b2 = last ? nB : cB + (size_t)(t + 2) * kstep;
;             const char* a3 = a2 + kstep; const char* b3 = b2 + kstep;
;             PG8_LDB(B0, 0, 0); PG8_LDB(B1, 0, 1); PG8_SCHED; PG8_LDA(At, 0, 0); PG8_STAGEA(PG8_SA(1, 1), a1 + hstep);
;             PG8_WAIT_V(8); PG8_WAIT_L(0); PG8_BAR; PG8_MMA(0, 0, At, B0); PG8_MMA(0, 1, At, B1); PG8_BAR; PG8_SCHED;
;             PG8_LDA(At, 0, 1); PG8_STAGEB(PG8_SB(0, 0), b2); PG8_STAGEB(PG8_SB(0, 1), b2 + hstep); PG8_STAGEA(PG8_SA(0, 0), a2);
;             PG8_WAIT_V(8); PG8_WAIT_L(0); PG8_BAR; PG8_MMA(1, 0, At, B0); PG8_MMA(1, 1, At, B1); PG8_BAR; PG8_SCHED;
;             PG8_LDB(B0, 1, 0); PG8_LDB(B1, 1, 1); PG8_SCHED; PG8_LDA(At, 1, 0); PG8_STAGEA(PG8_SA(0, 1), a2 + hstep);
;             PG8_WAIT_V(8); PG8_WAIT_L(0); PG8_BAR; PG8_MMA(0, 0, At, B0); PG8_MMA(0, 1, At, B1); PG8_BAR; PG8_SCHED;
;             PG8_LDA(At, 1, 1); PG8_STAGEB(PG8_SB(1, 0), b3); PG8_STAGEB(PG8_SB(1, 1), b3 + hstep); PG8_STAGEA(PG8_SA(1, 0), a3);
;             PG8_WAIT_V(8); PG8_WAIT_L(0); PG8_BAR; PG8_MMA(1, 0, At, B0); PG8_MMA(1, 1, At, B1); PG8_BAR; PG8_SCHED;
	s_add_i32 s42, s79, s54
	v_lshl_add_u64 v[150:151], v[150:151], 0, s[22:23]
	s_mov_b32 m0, s42
	ds_read_b128 v[188:191], v154 offset:49152
	ds_read_b128 v[192:195], v238 offset:49152
	ds_read_b128 v[196:199], v154 offset:51200
	ds_read_b128 v[200:203], v238 offset:51200
	ds_read_b128 v[204:207], v154 offset:53248
	ds_read_b128 v[208:211], v238 offset:53248
	ds_read_b128 v[212:215], v154 offset:55296
	ds_read_b128 v[216:219], v238 offset:55296
	global_load_lds_dwordx4 v[150:151], off
	s_add_i32 m0, s42, 0x2000
	s_add_u32 s40, s40, 0xb0080
	v_lshl_add_u64 v[150:151], v[220:221], 0, s[22:23]
	s_addc_u32 s41, s41, 0
	s_add_i32 s42, s80, s54
	global_load_lds_dwordx4 v[150:151], off
	v_lshl_add_u64 v[150:151], s[40:41], 0, v[132:133]
	s_mov_b32 m0, s42
	s_nop 0
	global_load_lds_dwordx4 v[150:151], off
	v_lshl_add_u64 v[150:151], s[40:41], 0, v[136:137]
	s_add_i32 m0, s42, 0x2000
	s_nop 0
	global_load_lds_dwordx4 v[150:151], off
	v_lshl_add_u64 v[150:151], v[222:223], 0, s[22:23]
	s_mov_b32 m0, s69
	s_nop 0
	global_load_lds_dwordx4 v[150:151], off
	v_lshl_add_u64 v[150:151], v[224:225], 0, s[22:23]
	s_mov_b32 m0, s70
	s_nop 0
	global_load_lds_dwordx4 v[150:151], off
	s_waitcnt vmcnt(8)
	s_waitcnt lgkmcnt(0)
	s_barrier
	s_waitcnt lgkmcnt(0)
	v_mfma_f32_16x16x32_bf16 v[62:65], v[156:159], v[188:191], v[62:65]
	v_mfma_f32_16x16x32_bf16 v[58:61], v[164:167], v[188:191], v[58:61]
	v_mfma_f32_16x16x32_bf16 v[54:57], v[156:159], v[196:199], v[54:57]
	v_mfma_f32_16x16x32_bf16 v[50:53], v[164:167], v[196:199], v[50:53]
	v_mfma_f32_16x16x32_bf16 v[46:49], v[156:159], v[204:207], v[46:49]
	v_mfma_f32_16x16x32_bf16 v[42:45], v[164:167], v[204:207], v[42:45]
	v_mfma_f32_16x16x32_bf16 v[38:41], v[156:159], v[212:215], v[38:41]
	v_mfma_f32_16x16x32_bf16 v[34:37], v[164:167], v[212:215], v[34:37]
	v_mfma_f32_16x16x32_bf16 v[62:65], v[160:163], v[192:195], v[62:65]
	v_mfma_f32_16x16x32_bf16 v[58:61], v[168:171], v[192:195], v[58:61]
	v_mfma_f32_16x16x32_bf16 v[54:57], v[160:163], v[200:203], v[54:57]
	v_mfma_f32_16x16x32_bf16 v[50:53], v[168:171], v[200:203], v[50:53]
	v_mfma_f32_16x16x32_bf16 v[46:49], v[160:163], v[208:211], v[46:49]
	v_mfma_f32_16x16x32_bf16 v[42:45], v[168:171], v[208:211], v[42:45]
	v_mfma_f32_16x16x32_bf16 v[38:41], v[160:163], v[216:219], v[38:41]
	v_mfma_f32_16x16x32_bf16 v[34:37], v[168:171], v[216:219], v[34:37]
	v_mfma_f32_16x16x32_bf16 v[30:33], v[172:175], v[188:191], v[30:33]
	v_mfma_f32_16x16x32_bf16 v[26:29], v[180:183], v[188:191], v[26:29]
	v_mfma_f32_16x16x32_bf16 v[22:25], v[172:175], v[196:199], v[22:25]
	v_mfma_f32_16x16x32_bf16 v[18:21], v[180:183], v[196:199], v[18:21]
	v_mfma_f32_16x16x32_bf16 v[14:17], v[172:175], v[204:207], v[14:17]
	v_mfma_f32_16x16x32_bf16 v[10:13], v[180:183], v[204:207], v[10:13]
	v_mfma_f32_16x16x32_bf16 v[6:9], v[172:175], v[212:215], v[6:9]
	v_mfma_f32_16x16x32_bf16 v[2:5], v[180:183], v[212:215], v[2:5]
	v_mfma_f32_16x16x32_bf16 v[30:33], v[176:179], v[192:195], v[30:33]
	v_mfma_f32_16x16x32_bf16 v[26:29], v[184:187], v[192:195], v[26:29]
	v_mfma_f32_16x16x32_bf16 v[22:25], v[176:179], v[200:203], v[22:25]
	v_mfma_f32_16x16x32_bf16 v[18:21], v[184:187], v[200:203], v[18:21]
	v_mfma_f32_16x16x32_bf16 v[14:17], v[176:179], v[208:211], v[14:17]
	v_mfma_f32_16x16x32_bf16 v[10:13], v[184:187], v[208:211], v[10:13]
	v_mfma_f32_16x16x32_bf16 v[6:9], v[176:179], v[216:219], v[6:9]
	v_mfma_f32_16x16x32_bf16 v[2:5], v[184:187], v[216:219], v[2:5]
	s_barrier
	s_add_i32 s20, s20, 2
	s_add_u32 s38, s38, 0x100
	s_addc_u32 s39, s39, 0
	s_cmp_gt_u32 s20, 41
	s_cbranch_scc0 .LBB0_793
	s_branch .Lmy_kexit_3
.LBB0_793:
	v_add_u32_e32 v150, s71, v152
	v_add_u32_e32 v237, s71, v239
	ds_read_b128 v[156:159], v150
	ds_read_b128 v[160:163], v237
	ds_read_b128 v[164:167], v150 offset:2048
	ds_read_b128 v[168:171], v237 offset:2048
	v_add_u32_e32 v150, s72, v152
	v_add_u32_e32 v237, s72, v239
	s_add_u32 s40, s14, s38
	ds_read_b128 v[172:175], v150
	ds_read_b128 v[176:179], v237
	ds_read_b128 v[180:183], v150 offset:2048
	ds_read_b128 v[184:187], v237 offset:2048
	s_addc_u32 s41, s15, s39
	s_add_u32 s40, s40, 0x100
	s_addc_u32 s41, s41, 0
	s_add_u32 s79, s77, s38
	s_addc_u32 s80, s78, s39
	s_cmpk_eq_i32 s38, 0x1500
	s_cselect_b32 s43, s37, s41
	s_cselect_b32 s42, s36, s40
	s_cselect_b32 s41, s11, s80
	s_cselect_b32 s40, s10, s79
	v_lshl_add_u64 v[150:151], v[146:147], 0, s[38:39]
	s_add_i32 m0, s55, 0xc000
	ds_read_b128 v[188:191], v154
	ds_read_b128 v[192:195], v238
	ds_read_b128 v[196:199], v154 offset:2048
	ds_read_b128 v[200:203], v238 offset:2048
	ds_read_b128 v[204:207], v154 offset:4096
	ds_read_b128 v[208:211], v238 offset:4096
	ds_read_b128 v[212:215], v154 offset:6144
	ds_read_b128 v[216:219], v238 offset:6144
	global_load_lds_dwordx4 v[150:151], off
	v_lshl_add_u64 v[150:151], v[148:149], 0, s[38:39]
	s_add_i32 m0, s55, 0xe000
	s_nop 0
	global_load_lds_dwordx4 v[150:151], off
	s_waitcnt vmcnt(8)
	s_waitcnt lgkmcnt(0)
	s_barrier
; #define PG8_STAGEA(bufoff, gbase) PG8_STAGE_(bufoff, gbase, voffA)
; #define PG8_STAGEB(bufoff, gbase) PG8_STAGE_(bufoff, gbase, voffB)
; #define PG8_LDA(dst, b, h) do { _Pragma("unroll") for (int m = 0; m < 4; ++m) _Pragma("unroll") for (int k = 0; k < 2; ++k) dst[m][k] = *(const LAS bf16x8*)(lds + PG8_SA(b, h) + aoff + m * 2048 + k * 1024); } while (0)
; #define PG8_LDB(dst, b, h) do { _Pragma("unroll") for (int n = 0; n < 2; ++n) _Pragma("unroll") for (int k = 0; k < 2; ++k) dst[n][k] = *(const LAS bf16x8*)(lds + PG8_SB(b, h) + boff + n * 2048 + k * 1024); } while (0)
; #define PG8_MMA(ai, bj, At, Bt_) do { __builtin_amdgcn_s_setprio(1); _Pragma("unroll") for (int m = 0; m < 4; ++m) _Pragma("unroll") for (int n = 0; n < 2; ++n) _Pragma("unroll") for (int k = 0; k < 2; ++k) \
;         acc[ai][bj][m][n] = __builtin_amdgcn_mfma_f32_16x16x32_bf16(Bt_[n][k], At[m][k], acc[ai][bj][m][n], 0, 0, 0); __builtin_amdgcn_s_setprio(0); } while (0)
; #define PG8_WAIT_V(n) asm volatile("s_waitcnt vmcnt(" #n ")" ::: "memory")
; #define PG8_WAIT_L(n) asm volatile("s_waitcnt lgkmcnt(" #n ")" ::: "memory")
; #define PG8_BAR __builtin_amdgcn_s_barrier()
; #define PG8_SCHED __builtin_amdgcn_sched_barrier(0)
; template <int EK, int SK = -1>
; __device__ __forceinline__ void gemm_phase(LAS unsigned char* lds, const bf16_t* A, const bf16_t* Bt, int nM, int N, int K, const EpiArgs& E) {
;     ...
;             PG8_WAIT_V(8); PG8_WAIT_L(0); PG8_BAR; PG8_MMA(0, 0, At, B0); PG8_MMA(0, 1, At, B1); PG8_BAR; PG8_SCHED;
;             PG8_LDA(At, 0, 1); PG8_STAGEB(PG8_SB(0, 0), b2); PG8_STAGEB(PG8_SB(0, 1), b2 + hstep); PG8_STAGEA(PG8_SA(0, 0), a2);
;             PG8_WAIT_V(8); PG8_WAIT_L(0); PG8_BAR; PG8_MMA(1, 0, At, B0); PG8_MMA(1, 1, At, B1); PG8_BAR; PG8_SCHED;
;             PG8_LDB(B0, 1, 0); PG8_LDB(B1, 1, 1); PG8_SCHED; PG8_LDA(At, 1, 0); PG8_STAGEA(PG8_SA(0, 1), a2 + hstep);
;             PG8_WAIT_V(8); PG8_WAIT_L(0); PG8_BAR; PG8_MMA(0, 0, At, B0); PG8_MMA(0, 1, At, B1); PG8_BAR; PG8_SCHED;
	s_waitcnt lgkmcnt(0)
	v_mfma_f32_16x16x32_bf16 v[126:129], v[156:159], v[188:191], v[126:129]
	v_mfma_f32_16x16x32_bf16 v[122:125], v[164:167], v[188:191], v[122:125]
	v_mfma_f32_16x16x32_bf16 v[118:121], v[156:159], v[196:199], v[118:121]
	v_mfma_f32_16x16x32_bf16 v[114:117], v[164:167], v[196:199], v[114:117]
	v_mfma_f32_16x16x32_bf16 v[110:113], v[156:159], v[204:207], v[110:113]
	v_mfma_f32_16x16x32_bf16 v[106:109], v[164:167], v[204:207], v[106:109]
	v_mfma_f32_16x16x32_bf16 v[102:105], v[156:159], v[212:215], v[102:105]
	v_mfma_f32_16x16x32_bf16 v[98:101], v[164:167], v[212:215], v[98:101]
	v_mfma_f32_16x16x32_bf16 v[126:129], v[160:163], v[192:195], v[126:129]
	v_mfma_f32_16x16x32_bf16 v[122:125], v[168:171], v[192:195], v[122:125]
	v_mfma_f32_16x16x32_bf16 v[118:121], v[160:163], v[200:203], v[118:121]
	v_mfma_f32_16x16x32_bf16 v[114:117], v[168:171], v[200:203], v[114:117]
	v_mfma_f32_16x16x32_bf16 v[110:113], v[160:163], v[208:211], v[110:113]
	v_mfma_f32_16x16x32_bf16 v[106:109], v[168:171], v[208:211], v[106:109]
	v_mfma_f32_16x16x32_bf16 v[102:105], v[160:163], v[216:219], v[102:105]
	v_mfma_f32_16x16x32_bf16 v[98:101], v[168:171], v[216:219], v[98:101]
	v_mfma_f32_16x16x32_bf16 v[94:97], v[172:175], v[188:191], v[94:97]
	v_mfma_f32_16x16x32_bf16 v[90:93], v[180:183], v[188:191], v[90:93]
	v_mfma_f32_16x16x32_bf16 v[86:89], v[172:175], v[196:199], v[86:89]
	v_mfma_f32_16x16x32_bf16 v[82:85], v[180:183], v[196:199], v[82:85]
	v_mfma_f32_16x16x32_bf16 v[78:81], v[172:175], v[204:207], v[78:81]
	v_mfma_f32_16x16x32_bf16 v[74:77], v[180:183], v[204:207], v[74:77]
	v_mfma_f32_16x16x32_bf16 v[70:73], v[172:175], v[212:215], v[70:73]
	v_mfma_f32_16x16x32_bf16 v[66:69], v[180:183], v[212:215], v[66:69]
	v_mfma_f32_16x16x32_bf16 v[94:97], v[176:179], v[192:195], v[94:97]
	v_mfma_f32_16x16x32_bf16 v[90:93], v[184:187], v[192:195], v[90:93]
	v_mfma_f32_16x16x32_bf16 v[86:89], v[176:179], v[200:203], v[86:89]
	v_mfma_f32_16x16x32_bf16 v[82:85], v[184:187], v[200:203], v[82:85]
	v_mfma_f32_16x16x32_bf16 v[78:81], v[176:179], v[208:211], v[78:81]
	v_mfma_f32_16x16x32_bf16 v[74:77], v[184:187], v[208:211], v[74:77]
	v_mfma_f32_16x16x32_bf16 v[70:73], v[176:179], v[216:219], v[70:73]
	v_mfma_f32_16x16x32_bf16 v[66:69], v[184:187], v[216:219], v[66:69]
	s_barrier
	s_add_i32 s79, s71, s54
	v_lshl_add_u64 v[150:151], s[40:41], 0, v[132:133]
	s_mov_b32 m0, s79
	ds_read_b128 v[188:191], v154 offset:16384
	ds_read_b128 v[192:195], v238 offset:16384
	ds_read_b128 v[196:199], v154 offset:18432
	ds_read_b128 v[200:203], v238 offset:18432
	ds_read_b128 v[204:207], v154 offset:20480
	ds_read_b128 v[208:211], v238 offset:20480
	ds_read_b128 v[212:215], v154 offset:22528
	ds_read_b128 v[216:219], v238 offset:22528
	global_load_lds_dwordx4 v[150:151], off
	s_add_i32 m0, s79, 0x2000
	s_add_u32 s80, s40, 0xb0000
	v_lshl_add_u64 v[220:221], s[40:41], 0, v[136:137]
	s_addc_u32 s81, s41, 0
	s_add_i32 s79, s72, s54
	global_load_lds_dwordx4 v[220:221], off
	v_lshl_add_u64 v[222:223], s[80:81], 0, v[132:133]
	s_mov_b32 m0, s79
	v_lshl_add_u64 v[224:225], s[42:43], 0, v[134:135]
	global_load_lds_dwordx4 v[222:223], off
	v_lshl_add_u64 v[222:223], s[80:81], 0, v[136:137]
	s_add_i32 m0, s79, 0x2000
	s_nop 0
	global_load_lds_dwordx4 v[222:223], off
	v_lshl_add_u64 v[222:223], s[42:43], 0, v[130:131]
	s_mov_b32 m0, s55
	s_nop 0
	global_load_lds_dwordx4 v[222:223], off
	s_mov_b32 m0, s56
	s_nop 0
	global_load_lds_dwordx4 v[224:225], off
	s_waitcnt vmcnt(8)
	s_waitcnt lgkmcnt(0)
	s_barrier
	s_waitcnt lgkmcnt(0)
	v_mfma_f32_16x16x32_bf16 v[62:65], v[156:159], v[188:191], v[62:65]
	v_mfma_f32_16x16x32_bf16 v[58:61], v[164:167], v[188:191], v[58:61]
	v_mfma_f32_16x16x32_bf16 v[54:57], v[156:159], v[196:199], v[54:57]
	v_mfma_f32_16x16x32_bf16 v[50:53], v[164:167], v[196:199], v[50:53]
	v_mfma_f32_16x16x32_bf16 v[46:49], v[156:159], v[204:207], v[46:49]
	v_mfma_f32_16x16x32_bf16 v[42:45], v[164:167], v[204:207], v[42:45]
	v_mfma_f32_16x16x32_bf16 v[38:41], v[156:159], v[212:215], v[38:41]
	v_mfma_f32_16x16x32_bf16 v[34:37], v[164:167], v[212:215], v[34:37]
	v_mfma_f32_16x16x32_bf16 v[62:65], v[160:163], v[192:195], v[62:65]
	v_mfma_f32_16x16x32_bf16 v[58:61], v[168:171], v[192:195], v[58:61]
	v_mfma_f32_16x16x32_bf16 v[54:57], v[160:163], v[200:203], v[54:57]
	v_mfma_f32_16x16x32_bf16 v[50:53], v[168:171], v[200:203], v[50:53]
	v_mfma_f32_16x16x32_bf16 v[46:49], v[160:163], v[208:211], v[46:49]
	v_mfma_f32_16x16x32_bf16 v[42:45], v[168:171], v[208:211], v[42:45]
	v_mfma_f32_16x16x32_bf16 v[38:41], v[160:163], v[216:219], v[38:41]
	v_mfma_f32_16x16x32_bf16 v[34:37], v[168:171], v[216:219], v[34:37]
	v_mfma_f32_16x16x32_bf16 v[30:33], v[172:175], v[188:191], v[30:33]
	v_mfma_f32_16x16x32_bf16 v[26:29], v[180:183], v[188:191], v[26:29]
	v_mfma_f32_16x16x32_bf16 v[22:25], v[172:175], v[196:199], v[22:25]
	v_mfma_f32_16x16x32_bf16 v[18:21], v[180:183], v[196:199], v[18:21]
	v_mfma_f32_16x16x32_bf16 v[14:17], v[172:175], v[204:207], v[14:17]
	v_mfma_f32_16x16x32_bf16 v[10:13], v[180:183], v[204:207], v[10:13]
	v_mfma_f32_16x16x32_bf16 v[6:9], v[172:175], v[212:215], v[6:9]
	v_mfma_f32_16x16x32_bf16 v[2:5], v[180:183], v[212:215], v[2:5]
	v_mfma_f32_16x16x32_bf16 v[30:33], v[176:179], v[192:195], v[30:33]
	v_mfma_f32_16x16x32_bf16 v[26:29], v[184:187], v[192:195], v[26:29]
	v_mfma_f32_16x16x32_bf16 v[22:25], v[176:179], v[200:203], v[22:25]
	v_mfma_f32_16x16x32_bf16 v[18:21], v[184:187], v[200:203], v[18:21]
	v_mfma_f32_16x16x32_bf16 v[14:17], v[176:179], v[208:211], v[14:17]
	v_mfma_f32_16x16x32_bf16 v[10:13], v[184:187], v[208:211], v[10:13]
	v_mfma_f32_16x16x32_bf16 v[6:9], v[176:179], v[216:219], v[6:9]
	v_mfma_f32_16x16x32_bf16 v[2:5], v[184:187], v[216:219], v[2:5]
	s_barrier
; #define PG8_STAGEA(bufoff, gbase) PG8_STAGE_(bufoff, gbase, voffA)
; #define PG8_STAGEB(bufoff, gbase) PG8_STAGE_(bufoff, gbase, voffB)
; #define PG8_LDA(dst, b, h) do { _Pragma("unroll") for (int m = 0; m < 4; ++m) _Pragma("unroll") for (int k = 0; k < 2; ++k) dst[m][k] = *(const LAS bf16x8*)(lds + PG8_SA(b, h) + aoff + m * 2048 + k * 1024); } while (0)
; #define PG8_MMA(ai, bj, At, Bt_) do { __builtin_amdgcn_s_setprio(1); _Pragma("unroll") for (int m = 0; m < 4; ++m) _Pragma("unroll") for (int n = 0; n < 2; ++n) _Pragma("unroll") for (int k = 0; k < 2; ++k) \
;         acc[ai][bj][m][n] = __builtin_amdgcn_mfma_f32_16x16x32_bf16(Bt_[n][k], At[m][k], acc[ai][bj][m][n], 0, 0, 0); __builtin_amdgcn_s_setprio(0); } while (0)
; #define PG8_WAIT_V(n) asm volatile("s_waitcnt vmcnt(" #n ")" ::: "memory")
; #define PG8_WAIT_L(n) asm volatile("s_waitcnt lgkmcnt(" #n ")" ::: "memory")
; #define PG8_BAR __builtin_amdgcn_s_barrier()
; #define PG8_SCHED __builtin_amdgcn_sched_barrier(0)
; template <int EK, int SK = -1>
; __device__ __forceinline__ void gemm_phase(LAS unsigned char* lds, const bf16_t* A, const bf16_t* Bt, int nM, int N, int K, const EpiArgs& E) {
;     ...
;             PG8_WAIT_V(8); PG8_WAIT_L(0); PG8_BAR; PG8_MMA(0, 0, At, B0); PG8_MMA(0, 1, At, B1); PG8_BAR; PG8_SCHED;
;             PG8_LDA(At, 1, 1); PG8_STAGEB(PG8_SB(1, 0), b3); PG8_STAGEB(PG8_SB(1, 1), b3 + hstep); PG8_STAGEA(PG8_SA(1, 0), a3);
;             PG8_WAIT_V(8); PG8_WAIT_L(0); PG8_BAR; PG8_MMA(1, 0, At, B0); PG8_MMA(1, 1, At, B1); PG8_BAR; PG8_SCHED;
;         }
	s_add_i32 s79, 0, 0x18000
	s_add_i32 s80, 0, 0x1c000
	v_add_u32_e32 v168, s79, v152
	v_add_u32_e32 v236, s79, v239
	v_add_u32_e32 v184, s80, v152
	v_add_u32_e32 v237, s80, v239
	ds_read_b128 v[156:159], v168
	ds_read_b128 v[160:163], v236
	ds_read_b128 v[164:167], v168 offset:2048
	ds_read_b128 v[168:171], v236 offset:2048
	ds_read_b128 v[172:175], v184
	ds_read_b128 v[176:179], v237
	ds_read_b128 v[180:183], v184 offset:2048
	ds_read_b128 v[184:187], v237 offset:2048
	s_add_u32 s42, s42, 0xb0000
	s_addc_u32 s43, s43, 0
	s_mov_b32 m0, s57
	v_lshl_add_u64 v[226:227], s[42:43], 0, v[130:131]
	ds_read_b128 v[188:191], v154 offset:32768
	ds_read_b128 v[192:195], v238 offset:32768
	ds_read_b128 v[196:199], v154 offset:34816
	ds_read_b128 v[200:203], v238 offset:34816
	ds_read_b128 v[204:207], v154 offset:36864
	ds_read_b128 v[208:211], v238 offset:36864
	ds_read_b128 v[212:215], v154 offset:38912
	ds_read_b128 v[216:219], v238 offset:38912
	global_load_lds_dwordx4 v[226:227], off
	v_lshl_add_u64 v[226:227], s[42:43], 0, v[134:135]
	s_mov_b32 m0, s58
	s_nop 0
	global_load_lds_dwordx4 v[226:227], off
	s_waitcnt vmcnt(8)
	s_waitcnt lgkmcnt(0)
	s_barrier
	s_waitcnt lgkmcnt(0)
	v_mfma_f32_16x16x32_bf16 v[126:129], v[156:159], v[188:191], v[126:129]
	v_mfma_f32_16x16x32_bf16 v[122:125], v[164:167], v[188:191], v[122:125]
	v_mfma_f32_16x16x32_bf16 v[118:121], v[156:159], v[196:199], v[118:121]
	v_mfma_f32_16x16x32_bf16 v[114:117], v[164:167], v[196:199], v[114:117]
	v_mfma_f32_16x16x32_bf16 v[110:113], v[156:159], v[204:207], v[110:113]
	v_mfma_f32_16x16x32_bf16 v[106:109], v[164:167], v[204:207], v[106:109]
	v_mfma_f32_16x16x32_bf16 v[102:105], v[156:159], v[212:215], v[102:105]
	v_mfma_f32_16x16x32_bf16 v[98:101], v[164:167], v[212:215], v[98:101]
	v_mfma_f32_16x16x32_bf16 v[126:129], v[160:163], v[192:195], v[126:129]
	v_mfma_f32_16x16x32_bf16 v[122:125], v[168:171], v[192:195], v[122:125]
	v_mfma_f32_16x16x32_bf16 v[118:121], v[160:163], v[200:203], v[118:121]
	v_mfma_f32_16x16x32_bf16 v[114:117], v[168:171], v[200:203], v[114:117]
	v_mfma_f32_16x16x32_bf16 v[110:113], v[160:163], v[208:211], v[110:113]
	v_mfma_f32_16x16x32_bf16 v[106:109], v[168:171], v[208:211], v[106:109]
	v_mfma_f32_16x16x32_bf16 v[102:105], v[160:163], v[216:219], v[102:105]
	v_mfma_f32_16x16x32_bf16 v[98:101], v[168:171], v[216:219], v[98:101]
	v_mfma_f32_16x16x32_bf16 v[94:97], v[172:175], v[188:191], v[94:97]
	v_mfma_f32_16x16x32_bf16 v[90:93], v[180:183], v[188:191], v[90:93]
	v_mfma_f32_16x16x32_bf16 v[86:89], v[172:175], v[196:199], v[86:89]
	v_mfma_f32_16x16x32_bf16 v[82:85], v[180:183], v[196:199], v[82:85]
	v_mfma_f32_16x16x32_bf16 v[78:81], v[172:175], v[204:207], v[78:81]
	v_mfma_f32_16x16x32_bf16 v[74:77], v[180:183], v[204:207], v[74:77]
	v_mfma_f32_16x16x32_bf16 v[70:73], v[172:175], v[212:215], v[70:73]
	v_mfma_f32_16x16x32_bf16 v[66:69], v[180:183], v[212:215], v[66:69]
	v_mfma_f32_16x16x32_bf16 v[94:97], v[176:179], v[192:195], v[94:97]
	v_mfma_f32_16x16x32_bf16 v[90:93], v[184:187], v[192:195], v[90:93]
	v_mfma_f32_16x16x32_bf16 v[86:89], v[176:179], v[200:203], v[86:89]
	v_mfma_f32_16x16x32_bf16 v[82:85], v[184:187], v[200:203], v[82:85]
	v_mfma_f32_16x16x32_bf16 v[78:81], v[176:179], v[208:211], v[78:81]
	v_mfma_f32_16x16x32_bf16 v[74:77], v[184:187], v[208:211], v[74:77]
	v_mfma_f32_16x16x32_bf16 v[70:73], v[176:179], v[216:219], v[70:73]
	v_mfma_f32_16x16x32_bf16 v[66:69], v[184:187], v[216:219], v[66:69]
	s_barrier
	s_add_i32 s42, s79, s54
	v_lshl_add_u64 v[150:151], v[150:151], 0, s[22:23]
	s_mov_b32 m0, s42
	ds_read_b128 v[188:191], v154 offset:49152
	ds_read_b128 v[192:195], v238 offset:49152
	ds_read_b128 v[196:199], v154 offset:51200
	ds_read_b128 v[200:203], v238 offset:51200
	ds_read_b128 v[204:207], v154 offset:53248
	ds_read_b128 v[208:211], v238 offset:53248
	ds_read_b128 v[212:215], v154 offset:55296
	ds_read_b128 v[216:219], v238 offset:55296
	global_load_lds_dwordx4 v[150:151], off
	s_add_i32 m0, s42, 0x2000
	s_add_u32 s40, s40, 0xb0080
	v_lshl_add_u64 v[150:151], v[220:221], 0, s[22:23]
	s_addc_u32 s41, s41, 0
	s_add_i32 s42, s80, s54
	global_load_lds_dwordx4 v[150:151], off
	v_lshl_add_u64 v[150:151], s[40:41], 0, v[132:133]
	s_mov_b32 m0, s42
	s_nop 0
	global_load_lds_dwordx4 v[150:151], off
	v_lshl_add_u64 v[150:151], s[40:41], 0, v[136:137]
	s_add_i32 m0, s42, 0x2000
	s_nop 0
	global_load_lds_dwordx4 v[150:151], off
	v_lshl_add_u64 v[150:151], v[222:223], 0, s[22:23]
	s_mov_b32 m0, s69
	s_nop 0
	global_load_lds_dwordx4 v[150:151], off
	v_lshl_add_u64 v[150:151], v[224:225], 0, s[22:23]
	s_mov_b32 m0, s70
	s_nop 0
	global_load_lds_dwordx4 v[150:151], off
	s_waitcnt vmcnt(8)
	s_waitcnt lgkmcnt(0)
	s_barrier
	s_waitcnt lgkmcnt(0)
	v_mfma_f32_16x16x32_bf16 v[62:65], v[156:159], v[188:191], v[62:65]
	v_mfma_f32_16x16x32_bf16 v[58:61], v[164:167], v[188:191], v[58:61]
	v_mfma_f32_16x16x32_bf16 v[54:57], v[156:159], v[196:199], v[54:57]
	v_mfma_f32_16x16x32_bf16 v[50:53], v[164:167], v[196:199], v[50:53]
	v_mfma_f32_16x16x32_bf16 v[46:49], v[156:159], v[204:207], v[46:49]
	v_mfma_f32_16x16x32_bf16 v[42:45], v[164:167], v[204:207], v[42:45]
	v_mfma_f32_16x16x32_bf16 v[38:41], v[156:159], v[212:215], v[38:41]
	v_mfma_f32_16x16x32_bf16 v[34:37], v[164:167], v[212:215], v[34:37]
	v_mfma_f32_16x16x32_bf16 v[62:65], v[160:163], v[192:195], v[62:65]
	v_mfma_f32_16x16x32_bf16 v[58:61], v[168:171], v[192:195], v[58:61]
	v_mfma_f32_16x16x32_bf16 v[54:57], v[160:163], v[200:203], v[54:57]
	v_mfma_f32_16x16x32_bf16 v[50:53], v[168:171], v[200:203], v[50:53]
	v_mfma_f32_16x16x32_bf16 v[46:49], v[160:163], v[208:211], v[46:49]
	v_mfma_f32_16x16x32_bf16 v[42:45], v[168:171], v[208:211], v[42:45]
	v_mfma_f32_16x16x32_bf16 v[38:41], v[160:163], v[216:219], v[38:41]
	v_mfma_f32_16x16x32_bf16 v[34:37], v[168:171], v[216:219], v[34:37]
	v_mfma_f32_16x16x32_bf16 v[30:33], v[172:175], v[188:191], v[30:33]
	v_mfma_f32_16x16x32_bf16 v[26:29], v[180:183], v[188:191], v[26:29]
	v_mfma_f32_16x16x32_bf16 v[22:25], v[172:175], v[196:199], v[22:25]
	v_mfma_f32_16x16x32_bf16 v[18:21], v[180:183], v[196:199], v[18:21]
	v_mfma_f32_16x16x32_bf16 v[14:17], v[172:175], v[204:207], v[14:17]
	v_mfma_f32_16x16x32_bf16 v[10:13], v[180:183], v[204:207], v[10:13]
	v_mfma_f32_16x16x32_bf16 v[6:9], v[172:175], v[212:215], v[6:9]
	v_mfma_f32_16x16x32_bf16 v[2:5], v[180:183], v[212:215], v[2:5]
	v_mfma_f32_16x16x32_bf16 v[30:33], v[176:179], v[192:195], v[30:33]
	v_mfma_f32_16x16x32_bf16 v[26:29], v[184:187], v[192:195], v[26:29]
	v_mfma_f32_16x16x32_bf16 v[22:25], v[176:179], v[200:203], v[22:25]
	v_mfma_f32_16x16x32_bf16 v[18:21], v[184:187], v[200:203], v[18:21]
	v_mfma_f32_16x16x32_bf16 v[14:17], v[176:179], v[208:211], v[14:17]
	v_mfma_f32_16x16x32_bf16 v[10:13], v[184:187], v[208:211], v[10:13]
	v_mfma_f32_16x16x32_bf16 v[6:9], v[176:179], v[216:219], v[6:9]
	v_mfma_f32_16x16x32_bf16 v[2:5], v[184:187], v[216:219], v[2:5]
	s_barrier
	s_add_i32 s20, s20, 2
	s_add_u32 s38, s38, 0x100
	s_addc_u32 s39, s39, 0
	s_cmp_gt_u32 s20, 41
	s_cbranch_scc0 .LBB0_793

; __global__ void __launch_bounds__(512, 2) mega_fwd(Params p) {
	.amdhsa_kernel _Z8mega_fwd6Params
		.amdhsa_group_segment_fixed_size 0
		.amdhsa_private_segment_fixed_size 0
		.amdhsa_kernarg_size 440
		.amdhsa_user_sgpr_count 2
		.amdhsa_user_sgpr_dispatch_ptr 0
		.amdhsa_user_sgpr_queue_ptr 0
		.amdhsa_user_sgpr_kernarg_segment_ptr 1
		.amdhsa_user_sgpr_dispatch_id 0
		.amdhsa_user_sgpr_kernarg_preload_length 0
		.amdhsa_user_sgpr_kernarg_preload_offset 0
		.amdhsa_user_sgpr_private_segment_size 0
		.amdhsa_uses_dynamic_stack 0
		.amdhsa_enable_private_segment 0
		.amdhsa_system_sgpr_workgroup_id_x 1
		.amdhsa_system_sgpr_workgroup_id_y 0
		.amdhsa_system_sgpr_workgroup_id_z 0
		.amdhsa_system_sgpr_workgroup_info 0
		.amdhsa_system_vgpr_workitem_id 0
		.amdhsa_next_free_vgpr 240
		.amdhsa_next_free_sgpr 102
		.amdhsa_accum_offset 240
		.amdhsa_reserve_vcc 1
		.amdhsa_float_round_mode_32 0
		.amdhsa_float_round_mode_16_64 0
		.amdhsa_float_denorm_mode_32 3
		.amdhsa_float_denorm_mode_16_64 3
		.amdhsa_dx10_clamp 1
		.amdhsa_ieee_mode 1
		.amdhsa_fp16_overflow 0
		.amdhsa_tg_split 0
		.amdhsa_exception_fp_ieee_invalid_op 0
		.amdhsa_exception_fp_denorm_src 0
		.amdhsa_exception_fp_ieee_div_zero 0
		.amdhsa_exception_fp_ieee_overflow 0
		.amdhsa_exception_fp_ieee_underflow 0
		.amdhsa_exception_fp_ieee_inexact 0
		.amdhsa_exception_int_div_zero 0
	.end_amdhsa_kernel

; __global__ void __launch_bounds__(512, 2) mega_fwd(Params p) {
amdhsa.kernels:
  - .agpr_count:     0
    .args:
      - .offset:         0
        .size:           184
        .value_kind:     by_value
      - .offset:         184
        .size:           4
        .value_kind:     hidden_block_count_x
      - .offset:         188
        .size:           4
        .value_kind:     hidden_block_count_y
      - .offset:         192
        .size:           4
        .value_kind:     hidden_block_count_z
      - .offset:         196
        .size:           2
        .value_kind:     hidden_group_size_x
      - .offset:         198
        .size:           2
        .value_kind:     hidden_group_size_y
      - .offset:         200
        .size:           2
        .value_kind:     hidden_group_size_z
      - .offset:         202
        .size:           2
        .value_kind:     hidden_remainder_x
      - .offset:         204
        .size:           2
        .value_kind:     hidden_remainder_y
      - .offset:         206
        .size:           2
        .value_kind:     hidden_remainder_z
      - .offset:         224
        .size:           8
        .value_kind:     hidden_global_offset_x
      - .offset:         232
        .size:           8
        .value_kind:     hidden_global_offset_y
      - .offset:         240
        .size:           8
        .value_kind:     hidden_global_offset_z
      - .offset:         248
        .size:           2
        .value_kind:     hidden_grid_dims
      - .offset:         304
        .size:           4
        .value_kind:     hidden_dynamic_lds_size
    .group_segment_fixed_size: 0
    .kernarg_segment_align: 8
    .kernarg_segment_size: 440
    .language:       OpenCL C
    .language_version:
      - 2
      - 0
    .max_flat_workgroup_size: 512
    .name:           _Z8mega_fwd6Params
    .private_segment_fixed_size: 0
    .sgpr_count:     108
    .sgpr_spill_count: 0
    .symbol:         _Z8mega_fwd6Params.kd
    .uniform_work_group_size: 1
    .uses_dynamic_stack: false
    .vgpr_count:     240
    .vgpr_spill_count: 0
    .wavefront_size: 64
